# grid barrier: workgroups that are not their XCD's last arriver poll the global generation word directly instead of a per-XCD generation word forwarded by the XCD leader (one hop fewer); the forwarding
# speedup vs baseline: 1.0151x; 1.0004x over previous
; __device__ __forceinline__ unsigned xb_ld(unsigned* p)              { return __hip_atomic_load(p, __ATOMIC_RELAXED, __HIP_MEMORY_SCOPE_AGENT); }
; __device__ __forceinline__ unsigned xb_add(unsigned* p, unsigned v) { return __hip_atomic_fetch_add(p, v, __ATOMIC_RELAXED, __HIP_MEMORY_SCOPE_AGENT); }
; #define XB_SPIN(cond, bar) do { unsigned _sp = 0; while (cond) { __builtin_amdgcn_s_sleep(1); \
;     if ((++_sp & 255u) == 0u) { if (xb_ld(&(bar)[XB_TMO])) break; if (_sp > XB_SPIN_CAP) { atomicAdd(&(bar)[XB_TMO], 1u); break; } } } } while (0)
; __device__ __forceinline__ void xcd_barrier(unsigned* bar, volatile LAS unsigned* st) {
;     ...
;         const unsigned old = xb_add(&bar[XB_XSUB(x)], 1u);
;         const unsigned gen = old / nloc;
;         if (old + 1u == (gen + 1u) * nloc) {
;             __builtin_amdgcn_fence(__ATOMIC_RELEASE, "agent");
;             asm volatile("s_waitcnt vmcnt(0)" ::: "memory");
;             const unsigned og = xb_add(&bar[XB_TOP], 1u);
;             const unsigned tg = og / nx;
;             if (og + 1u == (tg + 1u) * nx) xb_add(&bar[XB_TOPGEN], 1u);
;             else XB_SPIN(xb_ld(&bar[XB_TOPGEN]) == tg, bar);
;             __builtin_amdgcn_fence(__ATOMIC_ACQUIRE, "agent");
;             xb_add(&bar[XB_XGEN(x)], 1u);
;             asm volatile("s_waitcnt vmcnt(0)" ::: "memory");
;         } else {
;             XB_SPIN(xb_ld(&bar[XB_XGEN(x)]) == gen, bar);
.LBB0_27:
	s_lshl_b32 s0, s0, 8
	s_add_u32 s1, s72, s0
	s_addc_u32 s0, s73, 0
	v_mov_b32_e32 v1, s1
	v_add_co_u32_e32 v6, vcc, 0x1000, v1
	v_mov_b32_e32 v1, s0
	s_nop 0
	v_addc_co_u32_e32 v7, vcc, 0, v1, vcc
	flat_atomic_add v1, v[6:7], v203 offset:1024 sc0
	v_cvt_f32_u32_e32 v3, v4
	v_sub_u32_e32 v5, 0, v4
	v_rcp_iflag_f32_e32 v3, v3
	s_nop 0
	v_mul_f32_e32 v3, 0x4f7ffffe, v3
	v_cvt_u32_f32_e32 v3, v3
	v_mul_lo_u32 v5, v5, v3
	v_mul_hi_u32 v5, v3, v5
	v_add_u32_e32 v3, v3, v5
	s_waitcnt vmcnt(0) lgkmcnt(0)
	v_mul_hi_u32 v3, v1, v3
	v_mul_lo_u32 v5, v3, v4
	v_add_u32_e32 v6, 1, v1
	v_sub_u32_e32 v1, v1, v5
	v_add_u32_e32 v7, 1, v3
	v_sub_u32_e32 v5, v1, v4
	v_cmp_ge_u32_e32 vcc, v1, v4
	s_nop 1
	v_cndmask_b32_e32 v3, v3, v7, vcc
	v_cndmask_b32_e32 v1, v1, v5, vcc
	v_add_u32_e32 v5, 1, v3
	v_cmp_ge_u32_e32 vcc, v1, v4
	s_nop 1
	v_cndmask_b32_e32 v1, v3, v5, vcc
	v_mad_u64_u32 v[4:5], s[2:3], v4, v1, v[4:5]
	v_cmp_ne_u32_e32 vcc, v6, v4
	s_and_saveexec_b64 s[2:3], vcc
	s_xor_b64 s[4:5], exec, s[2:3]
	s_cbranch_execz .LBB0_40
	v_mov_b32_e32 v0, s72
	v_add_co_u32_e32 v4, vcc, 0x3100, v0
	v_mov_b32_e32 v0, s73
	s_nop 0
	v_addc_co_u32_e32 v5, vcc, 0, v0, vcc
	flat_load_dword v0, v[4:5] offset:1024 sc1
	s_add_u32 s8, s72, 0x3500
	s_addc_u32 s9, s73, 0
	s_waitcnt vmcnt(0) lgkmcnt(0)
	v_cmp_eq_u32_e32 vcc, v0, v1
	s_and_saveexec_b64 s[6:7], vcc
	s_cbranch_execz .LBB0_39
	s_mov_b32 s2, 1
	s_mov_b64 s[10:11], 0
	s_branch .LBB0_31

; __device__ __forceinline__ unsigned xb_ld(unsigned* p)              { return __hip_atomic_load(p, __ATOMIC_RELAXED, __HIP_MEMORY_SCOPE_AGENT); }
; __device__ __forceinline__ unsigned xb_add(unsigned* p, unsigned v) { return __hip_atomic_fetch_add(p, v, __ATOMIC_RELAXED, __HIP_MEMORY_SCOPE_AGENT); }
; #define XB_SPIN(cond, bar) do { unsigned _sp = 0; while (cond) { __builtin_amdgcn_s_sleep(1); \
;     if ((++_sp & 255u) == 0u) { if (xb_ld(&(bar)[XB_TMO])) break; if (_sp > XB_SPIN_CAP) { atomicAdd(&(bar)[XB_TMO], 1u); break; } } } } while (0)
; __device__ __forceinline__ void xcd_barrier(unsigned* bar, volatile LAS unsigned* st) {
;     ...
;             const unsigned og = xb_add(&bar[XB_TOP], 1u);
;             const unsigned tg = og / nx;
;             if (og + 1u == (tg + 1u) * nx) xb_add(&bar[XB_TOPGEN], 1u);
;             else XB_SPIN(xb_ld(&bar[XB_TOPGEN]) == tg, bar);
;             __builtin_amdgcn_fence(__ATOMIC_ACQUIRE, "agent");
;             xb_add(&bar[XB_XGEN(x)], 1u);
;             asm volatile("s_waitcnt vmcnt(0)" ::: "memory");
.LBB0_55:
	s_or_b64 exec, exec, s[4:5]
	v_mov_b32_e32 v0, s1
	v_add_co_u32_e32 v0, vcc, 0x2000, v0
	v_mov_b32_e32 v1, s0
	s_nop 0
	v_addc_co_u32_e32 v1, vcc, 0, v1, vcc
	s_waitcnt vmcnt(0) lgkmcnt(0)
	buffer_inv sc1
	s_waitcnt vmcnt(0)
